# nt on P0b w_ada and P1 x-row streaming loads, on top of P6 residual nt
# speedup vs baseline: 1.0088x; 1.0088x over previous
.LBB0_789:
	v_lshl_or_b32 v2, s74, 8, v195
	s_ashr_i32 s44, s73, 5
	v_lshl_add_u32 v24, s73, 8, v1
	s_mul_hi_i32 s45, s44, 0x18000
	s_mul_i32 s44, s44, 0x18000
	v_ashrrev_i32_e32 v3, 31, v2
	v_ashrrev_i32_e32 v25, 31, v24
	v_or_b32_e32 v186, 16, v24
	v_or_b32_e32 v208, 32, v24
	s_add_u32 s44, s64, s44
	v_lshlrev_b64 v[18:19], 2, v[2:3]
	v_lshlrev_b64 v[22:23], 14, v[24:25]
	v_ashrrev_i32_e32 v187, 31, v186
	v_ashrrev_i32_e32 v209, 31, v208
	v_or_b32_e32 v24, 48, v24
	s_addc_u32 s45, s65, s45
	v_lshl_add_u64 v[20:21], s[10:11], 0, v[18:19]
	v_lshlrev_b64 v[240:241], 14, v[186:187]
	v_lshlrev_b64 v[242:243], 14, v[208:209]
	v_ashrrev_i32_e32 v25, 31, v24
	v_lshl_add_u64 v[2:3], s[44:45], 0, v[18:19]
	v_lshl_add_u64 v[166:167], v[20:21], 0, v[22:23]
	v_lshl_add_u64 v[204:205], v[20:21], 0, v[240:241]
	v_lshl_add_u64 v[220:221], v[20:21], 0, v[242:243]
	v_lshlrev_b64 v[24:25], 14, v[24:25]
	global_load_dwordx4 v[14:17], v[2:3], off nt
	global_load_dwordx4 v[10:13], v[2:3], off offset:64 nt
	global_load_dwordx4 v[6:9], v[2:3], off offset:512 nt
	s_nop 0
	global_load_dwordx4 v[2:5], v[2:3], off offset:576 nt
	s_nop 0
	global_load_dwordx4 v[154:157], v[166:167], off nt
	global_load_dwordx4 v[158:161], v[166:167], off offset:64 nt
	global_load_dwordx4 v[162:165], v[166:167], off offset:512 nt
	s_nop 0
	global_load_dwordx4 v[166:169], v[166:167], off offset:576 nt
	s_nop 0
	global_load_dwordx4 v[186:189], v[204:205], off nt
	global_load_dwordx4 v[190:193], v[204:205], off offset:64 nt
	global_load_dwordx4 v[200:203], v[204:205], off offset:512 nt
	s_nop 0
	global_load_dwordx4 v[204:207], v[204:205], off offset:576 nt
	s_nop 0
	global_load_dwordx4 v[208:211], v[220:221], off nt
	global_load_dwordx4 v[212:215], v[220:221], off offset:64 nt
	global_load_dwordx4 v[216:219], v[220:221], off offset:512 nt
	s_nop 0
	global_load_dwordx4 v[220:223], v[220:221], off offset:576 nt
	v_lshl_add_u64 v[236:237], v[20:21], 0, v[24:25]
	global_load_dwordx4 v[224:227], v[236:237], off nt
	global_load_dwordx4 v[228:231], v[236:237], off offset:64 nt
	global_load_dwordx4 v[232:235], v[236:237], off offset:512 nt
	s_nop 0
	global_load_dwordx4 v[236:239], v[236:237], off offset:576 nt
	v_lshl_add_u64 v[244:245], s[12:13], 0, v[22:23]
	v_lshl_add_u64 v[244:245], v[244:245], 0, v[18:19]
	v_lshl_add_u64 v[240:241], s[12:13], 0, v[240:241]
	v_lshl_add_u64 v[242:243], s[12:13], 0, v[242:243]
	v_lshl_add_u64 v[24:25], s[12:13], 0, v[24:25]
	v_lshl_add_u64 v[240:241], v[240:241], 0, v[18:19]
	v_lshl_add_u64 v[242:243], v[242:243], 0, v[18:19]
	v_lshl_add_u64 v[24:25], v[24:25], 0, v[18:19]
	s_and_b64 vcc, exec, s[6:7]
	s_mov_b64 s[6:7], -1
	s_waitcnt vmcnt(0)
	v_pk_fma_f32 v[152:153], v[152:153], v[16:17], v[156:157]
	v_pk_fma_f32 v[150:151], v[150:151], v[14:15], v[154:155]
	v_pk_fma_f32 v[148:149], v[148:149], v[12:13], v[160:161]
	v_pk_fma_f32 v[146:147], v[146:147], v[10:11], v[158:159]
	v_pk_fma_f32 v[132:133], v[132:133], v[8:9], v[164:165]
	v_pk_fma_f32 v[104:105], v[104:105], v[4:5], v[222:223]
	v_pk_fma_f32 v[102:103], v[102:103], v[2:3], v[220:221]
	v_pk_fma_f32 v[130:131], v[130:131], v[6:7], v[162:163]
	v_pk_fma_f32 v[128:129], v[128:129], v[4:5], v[168:169]
	v_pk_fma_f32 v[126:127], v[126:127], v[2:3], v[166:167]
	v_pk_fma_f32 v[144:145], v[144:145], v[16:17], v[188:189]
	v_pk_fma_f32 v[142:143], v[142:143], v[14:15], v[186:187]
	v_pk_fma_f32 v[140:141], v[140:141], v[12:13], v[192:193]
	v_pk_fma_f32 v[138:139], v[138:139], v[10:11], v[190:191]
	v_pk_fma_f32 v[120:121], v[120:121], v[8:9], v[202:203]
	v_pk_fma_f32 v[118:119], v[118:119], v[6:7], v[200:201]
	v_pk_fma_f32 v[116:117], v[116:117], v[4:5], v[206:207]
	v_pk_fma_f32 v[114:115], v[114:115], v[2:3], v[204:205]
	v_pk_fma_f32 v[136:137], v[136:137], v[16:17], v[210:211]
	v_pk_fma_f32 v[134:135], v[134:135], v[14:15], v[208:209]
	v_pk_fma_f32 v[124:125], v[124:125], v[12:13], v[214:215]
	v_pk_fma_f32 v[122:123], v[122:123], v[10:11], v[212:213]
	v_pk_fma_f32 v[112:113], v[112:113], v[8:9], v[218:219]
	v_pk_fma_f32 v[110:111], v[110:111], v[6:7], v[216:217]
	global_store_dwordx4 v[244:245], v[150:153], off
	global_store_dwordx4 v[244:245], v[146:149], off offset:64
	global_store_dwordx4 v[244:245], v[130:133], off offset:512
	global_store_dwordx4 v[244:245], v[126:129], off offset:576
	global_store_dwordx4 v[240:241], v[142:145], off
	global_store_dwordx4 v[240:241], v[138:141], off offset:64
	global_store_dwordx4 v[240:241], v[118:121], off offset:512
	global_store_dwordx4 v[240:241], v[114:117], off offset:576
	global_store_dwordx4 v[242:243], v[134:137], off
	global_store_dwordx4 v[242:243], v[122:125], off offset:64
	global_store_dwordx4 v[242:243], v[110:113], off offset:512
	global_store_dwordx4 v[242:243], v[102:105], off offset:576
	v_pk_fma_f32 v[100:101], v[100:101], v[12:13], v[230:231]
	v_pk_fma_f32 v[98:99], v[98:99], v[10:11], v[228:229]
	v_pk_fma_f32 v[104:105], v[108:109], v[16:17], v[226:227]
	v_pk_fma_f32 v[102:103], v[106:107], v[14:15], v[224:225]
	v_pk_fma_f32 v[96:97], v[96:97], v[8:9], v[234:235]
	v_pk_fma_f32 v[94:95], v[94:95], v[6:7], v[232:233]
	v_pk_fma_f32 v[92:93], v[92:93], v[4:5], v[238:239]
	v_pk_fma_f32 v[90:91], v[90:91], v[2:3], v[236:237]
	global_store_dwordx4 v[24:25], v[102:105], off
	global_store_dwordx4 v[24:25], v[98:101], off offset:64
	global_store_dwordx4 v[24:25], v[94:97], off offset:512
	global_store_dwordx4 v[24:25], v[90:93], off offset:576
	v_lshl_add_u64 v[24:25], v[22:23], 0, s[38:39]
	v_lshl_add_u64 v[150:151], v[22:23], 0, s[40:41]
	v_lshl_add_u64 v[152:153], v[22:23], 0, s[42:43]
	v_lshl_add_u64 v[154:155], v[22:23], 0, s[50:51]
	v_lshl_add_u64 v[102:103], v[20:21], 0, v[24:25]
	v_lshl_add_u64 v[118:119], v[20:21], 0, v[150:151]
	v_lshl_add_u64 v[134:135], v[20:21], 0, v[152:153]
	v_lshl_add_u64 v[146:147], v[20:21], 0, v[154:155]
	global_load_dwordx4 v[90:93], v[102:103], off nt
	global_load_dwordx4 v[94:97], v[102:103], off offset:64 nt
	global_load_dwordx4 v[98:101], v[102:103], off offset:512 nt
	s_nop 0
	global_load_dwordx4 v[102:105], v[102:103], off offset:576 nt
	s_nop 0
	global_load_dwordx4 v[106:109], v[118:119], off nt
	global_load_dwordx4 v[110:113], v[118:119], off offset:64 nt
	global_load_dwordx4 v[114:117], v[118:119], off offset:512 nt
	s_nop 0
	global_load_dwordx4 v[118:121], v[118:119], off offset:576 nt
	s_nop 0
	global_load_dwordx4 v[122:125], v[134:135], off nt
	global_load_dwordx4 v[126:129], v[134:135], off offset:64 nt
	global_load_dwordx4 v[130:133], v[134:135], off offset:512 nt
	s_nop 0
	global_load_dwordx4 v[134:137], v[134:135], off offset:576 nt
	s_nop 0
	global_load_dwordx4 v[20:23], v[146:147], off nt
	global_load_dwordx4 v[138:141], v[146:147], off offset:64 nt
	global_load_dwordx4 v[142:145], v[146:147], off offset:512 nt
	s_nop 0
	global_load_dwordx4 v[146:149], v[146:147], off offset:576 nt
	v_lshl_add_u64 v[24:25], s[12:13], 0, v[24:25]
	v_lshl_add_u64 v[150:151], s[12:13], 0, v[150:151]
	v_lshl_add_u64 v[152:153], s[12:13], 0, v[152:153]
	v_lshl_add_u64 v[24:25], v[24:25], 0, v[18:19]
	v_lshl_add_u64 v[150:151], v[150:151], 0, v[18:19]
	v_lshl_add_u64 v[152:153], v[152:153], 0, v[18:19]
	s_waitcnt vmcnt(15)
	v_pk_fma_f32 v[86:87], v[86:87], v[14:15], v[90:91]
	s_waitcnt vmcnt(11)
	v_pk_fma_f32 v[78:79], v[78:79], v[14:15], v[106:107]
	s_waitcnt vmcnt(7)
	v_pk_fma_f32 v[70:71], v[70:71], v[14:15], v[122:123]
	s_waitcnt vmcnt(3)
	v_pk_fma_f32 v[14:15], v[42:43], v[14:15], v[20:21]
	v_lshl_add_u64 v[20:21], s[12:13], 0, v[154:155]
	v_pk_fma_f32 v[88:89], v[88:89], v[16:17], v[92:93]
	v_pk_fma_f32 v[84:85], v[84:85], v[12:13], v[96:97]
	v_pk_fma_f32 v[82:83], v[82:83], v[10:11], v[94:95]
	v_pk_fma_f32 v[68:69], v[68:69], v[8:9], v[100:101]
	v_pk_fma_f32 v[66:67], v[66:67], v[6:7], v[98:99]
	v_pk_fma_f32 v[64:65], v[64:65], v[4:5], v[104:105]
	v_pk_fma_f32 v[62:63], v[62:63], v[2:3], v[102:103]
	v_pk_fma_f32 v[80:81], v[80:81], v[16:17], v[108:109]
	v_pk_fma_f32 v[76:77], v[76:77], v[12:13], v[112:113]
	v_pk_fma_f32 v[74:75], v[74:75], v[10:11], v[110:111]
	v_pk_fma_f32 v[56:57], v[56:57], v[8:9], v[116:117]
	v_pk_fma_f32 v[54:55], v[54:55], v[6:7], v[114:115]
	v_pk_fma_f32 v[52:53], v[52:53], v[4:5], v[120:121]
	v_pk_fma_f32 v[50:51], v[50:51], v[2:3], v[118:119]
	v_pk_fma_f32 v[72:73], v[72:73], v[16:17], v[124:125]
	v_pk_fma_f32 v[60:61], v[60:61], v[12:13], v[128:129]
	v_pk_fma_f32 v[58:59], v[58:59], v[10:11], v[126:127]
	v_pk_fma_f32 v[48:49], v[48:49], v[8:9], v[132:133]
	v_pk_fma_f32 v[46:47], v[46:47], v[6:7], v[130:131]
	v_pk_fma_f32 v[40:41], v[40:41], v[4:5], v[136:137]
	v_pk_fma_f32 v[38:39], v[38:39], v[2:3], v[134:135]
	v_pk_fma_f32 v[16:17], v[44:45], v[16:17], v[22:23]
	v_lshl_add_u64 v[18:19], v[20:21], 0, v[18:19]
	s_waitcnt vmcnt(2)
	v_pk_fma_f32 v[12:13], v[36:37], v[12:13], v[140:141]
	v_pk_fma_f32 v[10:11], v[34:35], v[10:11], v[138:139]
	s_waitcnt vmcnt(1)
	v_pk_fma_f32 v[8:9], v[32:33], v[8:9], v[144:145]
	v_pk_fma_f32 v[6:7], v[30:31], v[6:7], v[142:143]
	s_waitcnt vmcnt(0)
	v_pk_fma_f32 v[4:5], v[28:29], v[4:5], v[148:149]
	v_pk_fma_f32 v[2:3], v[26:27], v[2:3], v[146:147]
	global_store_dwordx4 v[24:25], v[86:89], off
	global_store_dwordx4 v[24:25], v[82:85], off offset:64
	global_store_dwordx4 v[24:25], v[66:69], off offset:512
	global_store_dwordx4 v[24:25], v[62:65], off offset:576
	global_store_dwordx4 v[150:151], v[78:81], off
	global_store_dwordx4 v[150:151], v[74:77], off offset:64
	global_store_dwordx4 v[150:151], v[54:57], off offset:512
	global_store_dwordx4 v[150:151], v[50:53], off offset:576
	global_store_dwordx4 v[152:153], v[70:73], off
	global_store_dwordx4 v[152:153], v[58:61], off offset:64
	global_store_dwordx4 v[152:153], v[46:49], off offset:512
	global_store_dwordx4 v[152:153], v[38:41], off offset:576
	global_store_dwordx4 v[18:19], v[14:17], off
	global_store_dwordx4 v[18:19], v[10:13], off offset:64
	global_store_dwordx4 v[18:19], v[6:9], off offset:512
	global_store_dwordx4 v[18:19], v[2:5], off offset:576
	s_cbranch_vccnz .LBB0_772
	s_nop 7
	s_andn2_b64 vcc, exec, s[16:17]
	s_cbranch_vccnz .LBB0_771
	s_barrier
	s_branch .LBB0_771
